# G2m epilogue first pass: the 8 HC tile loads (one load, vmcnt(0), compute per row group in the baseline) issued together up front into dead VGPRs, counted vmcnt(7-k) waits, unpack reads renamed
# speedup vs baseline: 1.0102x; 1.0102x over previous
.LBB0_743:
	v_and_b32_e32 v1, 64, v211
	s_lshl_b32 s0, s40, 7
	v_xor_b32_e32 v0, 16, v211
	v_add_u32_e32 v1, 64, v1
	s_or_b32 s0, s0, s61
	s_lshl_b32 s26, s2, 8
	v_cmp_lt_i32_e32 vcc, v0, v1
	v_lshl_add_u32 v146, v130, 3, s0
	s_add_i32 s0, s26, s77
	v_cndmask_b32_e32 v0, v211, v0, vcc
	v_add_u32_e32 v150, s0, v214
	v_lshlrev_b32_e32 v216, 2, v0
	v_xor_b32_e32 v0, 32, v211
	v_cmp_lt_i32_e32 vcc, v0, v1
	v_ashrrev_i32_e32 v151, 31, v150
	v_lshlrev_b64 v[154:155], 11, v[150:151]
	v_cndmask_b32_e32 v0, v211, v0, vcc
	v_ashrrev_i32_e32 v147, 31, v146
	v_lshlrev_b32_e32 v215, 2, v0
	v_lshl_add_u64 v[0:1], s[16:17], 0, v[154:155]
	v_lshl_add_u64 v[0:1], v[146:147], 1, v[0:1]
	v_cmp_eq_u32_e32 vcc, 0, v130
	global_load_dwordx4 v[220:223], v[0:1], off
	v_add_u32_e32 v224, 16, v150
	v_ashrrev_i32_e32 v225, 31, v224
	v_lshlrev_b64 v[224:225], 11, v[224:225]
	v_lshl_add_u64 v[224:225], s[16:17], 0, v[224:225]
	v_lshl_add_u64 v[224:225], v[146:147], 1, v[224:225]
	global_load_dwordx4 v[224:227], v[224:225], off
	v_add_u32_e32 v228, 32, v150
	v_ashrrev_i32_e32 v229, 31, v228
	v_lshlrev_b64 v[228:229], 11, v[228:229]
	v_lshl_add_u64 v[228:229], s[16:17], 0, v[228:229]
	v_lshl_add_u64 v[228:229], v[146:147], 1, v[228:229]
	global_load_dwordx4 v[228:231], v[228:229], off
	v_add_u32_e32 v232, 48, v150
	v_ashrrev_i32_e32 v233, 31, v232
	v_lshlrev_b64 v[232:233], 11, v[232:233]
	v_lshl_add_u64 v[232:233], s[16:17], 0, v[232:233]
	v_lshl_add_u64 v[232:233], v[146:147], 1, v[232:233]
	global_load_dwordx4 v[232:235], v[232:233], off
	v_add_u32_e32 v236, 128, v150
	v_ashrrev_i32_e32 v237, 31, v236
	v_lshlrev_b64 v[236:237], 11, v[236:237]
	v_lshl_add_u64 v[236:237], s[16:17], 0, v[236:237]
	v_lshl_add_u64 v[236:237], v[146:147], 1, v[236:237]
	global_load_dwordx4 v[236:239], v[236:237], off
	v_add_u32_e32 v242, 144, v150
	v_ashrrev_i32_e32 v243, 31, v242
	v_lshlrev_b64 v[242:243], 11, v[242:243]
	v_lshl_add_u64 v[242:243], s[16:17], 0, v[242:243]
	v_lshl_add_u64 v[242:243], v[146:147], 1, v[242:243]
	global_load_dwordx4 v[242:245], v[242:243], off
	v_add_u32_e32 v246, 160, v150
	v_ashrrev_i32_e32 v247, 31, v246
	v_lshlrev_b64 v[246:247], 11, v[246:247]
	v_lshl_add_u64 v[246:247], s[16:17], 0, v[246:247]
	v_lshl_add_u64 v[246:247], v[146:147], 1, v[246:247]
	global_load_dwordx4 v[246:249], v[246:247], off
	v_add_u32_e32 v250, 176, v150
	v_ashrrev_i32_e32 v251, 31, v250
	v_lshlrev_b64 v[250:251], 11, v[250:251]
	v_lshl_add_u64 v[250:251], s[16:17], 0, v[250:251]
	v_lshl_add_u64 v[250:251], v[146:147], 1, v[250:251]
	global_load_dwordx4 v[250:253], v[250:251], off
	v_mul_f32_e32 v0, 0xbfb8aa3b, v126
	v_mul_f32_e32 v1, 0xbfb8aa3b, v127
	v_exp_f32_e32 v0, v0
	v_exp_f32_e32 v1, v1
	v_mul_f32_e32 v122, 0xbfb8aa3b, v122
	v_mul_f32_e32 v123, 0xbfb8aa3b, v123
	v_add_f32_e32 v0, 1.0, v0
	v_add_f32_e32 v1, 1.0, v1
	v_rcp_f32_e32 v0, v0
	v_rcp_f32_e32 v1, v1
	v_exp_f32_e32 v122, v122
	v_exp_f32_e32 v123, v123
	v_add_u32_e32 v152, s96, v214
	v_add_f32_e32 v122, 1.0, v122
	v_add_f32_e32 v123, 1.0, v123
	v_rcp_f32_e32 v122, v122
	v_rcp_f32_e32 v123, v123
	s_waitcnt vmcnt(7)
	v_lshlrev_b32_e32 v126, 16, v220
	v_and_b32_e32 v127, 0xffff0000, v220
	v_pk_mul_f32 v[126:127], v[0:1], v[126:127]
	v_mul_f32_e32 v1, 0xbfb8aa3b, v129
	v_add_f32_e32 v0, 0, v126
	v_add_f32_e32 v130, v127, v0
	v_mul_f32_e32 v0, 0xbfb8aa3b, v128
	v_exp_f32_e32 v0, v0
	v_exp_f32_e32 v1, v1
	v_lshlrev_b32_e32 v128, 16, v221
	v_and_b32_e32 v129, 0xffff0000, v221
	v_add_f32_e32 v0, 1.0, v0
	v_add_f32_e32 v1, 1.0, v1
	v_rcp_f32_e32 v0, v0
	v_rcp_f32_e32 v1, v1
	s_nop 0
	v_pk_mul_f32 v[128:129], v[0:1], v[128:129]
	s_nop 0
	v_add_f32_e32 v131, v128, v130
	v_mul_f32_e32 v130, v126, v126
	v_mov_b32_e32 v0, v128
	v_mov_b32_e32 v1, v126
	v_fmac_f32_e32 v130, v127, v127
	v_pk_fma_f32 v[0:1], v[0:1], v[0:1], v[130:131] op_sel_hi:[1,1,0]
	v_add_f32_e32 v148, v129, v131
	v_lshlrev_b32_e32 v130, 16, v222
	v_and_b32_e32 v131, 0xffff0000, v222
	v_pk_mul_f32 v[130:131], v[122:123], v[130:131]
	v_mul_f32_e32 v132, v129, v129
	v_mov_b32_e32 v122, v130
	v_mov_b32_e32 v123, v129
	v_pk_add_f32 v[0:1], v[132:133], v[0:1] op_sel_hi:[0,1]
	v_pk_fma_f32 v[122:123], v[122:123], v[122:123], v[0:1]
	v_mul_f32_e32 v0, 0xbfb8aa3b, v124
	v_mul_f32_e32 v1, 0xbfb8aa3b, v125
	v_exp_f32_e32 v0, v0
	v_exp_f32_e32 v1, v1
	v_add_f32_e32 v148, v130, v148
	v_lshlrev_b32_e32 v124, 16, v223
	v_add_f32_e32 v0, 1.0, v0
	v_add_f32_e32 v1, 1.0, v1
	v_rcp_f32_e32 v0, v0
	v_rcp_f32_e32 v1, v1
	v_and_b32_e32 v125, 0xffff0000, v223
	v_add_f32_e32 v132, v131, v148
	v_pk_mul_f32 v[156:157], v[0:1], v[124:125]
	s_nop 0
	v_add_f32_e32 v0, v156, v132
	v_mul_f32_e32 v132, v131, v131
	v_mov_b32_e32 v124, v156
	v_mov_b32_e32 v125, v131
	v_pk_add_f32 v[122:123], v[132:133], v[122:123] op_sel_hi:[0,1]
	v_pk_fma_f32 v[122:123], v[124:125], v[124:125], v[122:123]
	v_pk_mul_f32 v[124:125], v[156:157], v[156:157]
	v_pk_mov_b32 v[122:123], v[156:157], v[122:123] op_sel:[1,0]
	v_mov_b32_e32 v1, v125
	v_pk_add_f32 v[0:1], v[122:123], v[0:1]
	ds_bpermute_b32 v122, v216, v0
	ds_bpermute_b32 v123, v216, v1
	s_waitcnt lgkmcnt(0)
	v_pk_add_f32 v[122:123], v[0:1], v[122:123]
	ds_bpermute_b32 v124, v215, v122
	ds_bpermute_b32 v125, v215, v123
	s_and_saveexec_b64 s[0:1], vcc
	s_cbranch_execz .LBB0_745
	v_lshl_add_u32 v0, v152, 3, 0
	v_add_u32_e32 v132, 0x20000, v0
	s_waitcnt lgkmcnt(0)
	v_pk_add_f32 v[0:1], v[122:123], v[124:125]
	ds_write_b64 v132, v[0:1]
.LBB0_745:
	s_or_b64 exec, exec, s[0:1]
	v_add_u32_e32 v0, 16, v150
	v_ashrrev_i32_e32 v1, 31, v0
	v_lshlrev_b64 v[192:193], 11, v[0:1]
	v_lshl_add_u64 v[0:1], s[16:17], 0, v[192:193]
	v_lshl_add_u64 v[0:1], v[146:147], 1, v[0:1]
	s_waitcnt lgkmcnt(0)
	s_nop 0
	v_mul_f32_e32 v0, 0xbfb8aa3b, v118
	v_mul_f32_e32 v1, 0xbfb8aa3b, v119
	v_exp_f32_e32 v0, v0
	v_exp_f32_e32 v1, v1
	v_mul_f32_e32 v114, 0xbfb8aa3b, v114
	v_mul_f32_e32 v115, 0xbfb8aa3b, v115
	v_add_f32_e32 v0, 1.0, v0
	v_add_f32_e32 v1, 1.0, v1
	v_rcp_f32_e32 v0, v0
	v_rcp_f32_e32 v1, v1
	v_exp_f32_e32 v114, v114
	v_exp_f32_e32 v115, v115
	v_lshl_add_u32 v217, v152, 3, s71
	v_add_f32_e32 v114, 1.0, v114
	v_add_f32_e32 v115, 1.0, v115
	v_rcp_f32_e32 v114, v114
	v_rcp_f32_e32 v115, v115
	s_waitcnt vmcnt(6)
	v_lshlrev_b32_e32 v118, 16, v224
	v_and_b32_e32 v119, 0xffff0000, v224
	v_pk_mul_f32 v[132:133], v[0:1], v[118:119]
	v_mul_f32_e32 v1, 0xbfb8aa3b, v121
	v_add_f32_e32 v0, 0, v132
	v_add_f32_e32 v122, v133, v0
	v_mul_f32_e32 v0, 0xbfb8aa3b, v120
	v_exp_f32_e32 v0, v0
	v_exp_f32_e32 v1, v1
	v_lshlrev_b32_e32 v118, 16, v225
	v_and_b32_e32 v119, 0xffff0000, v225
	v_add_f32_e32 v0, 1.0, v0
	v_add_f32_e32 v1, 1.0, v1
	v_rcp_f32_e32 v0, v0
	v_rcp_f32_e32 v1, v1
	s_nop 0
	v_pk_mul_f32 v[148:149], v[0:1], v[118:119]
	v_mul_f32_e32 v118, v132, v132
	v_add_f32_e32 v119, v148, v122
	v_mov_b32_e32 v0, v148
	v_mov_b32_e32 v1, v132
	v_fmac_f32_e32 v118, v133, v133
	v_pk_fma_f32 v[0:1], v[0:1], v[0:1], v[118:119] op_sel_hi:[1,1,0]
	v_add_f32_e32 v120, v149, v119
	v_lshlrev_b32_e32 v118, 16, v226
	v_and_b32_e32 v119, 0xffff0000, v226
	v_pk_mul_f32 v[158:159], v[114:115], v[118:119]
	v_mul_f32_e32 v118, v149, v149
	v_add_f32_e32 v119, v158, v120
	v_mov_b32_e32 v114, v158
	v_mov_b32_e32 v115, v149
	v_pk_add_f32 v[0:1], v[118:119], v[0:1] op_sel_hi:[0,1]
	v_pk_fma_f32 v[0:1], v[114:115], v[114:115], v[0:1]
	v_mul_f32_e32 v114, 0xbfb8aa3b, v116
	v_mul_f32_e32 v115, 0xbfb8aa3b, v117
	v_exp_f32_e32 v114, v114
	v_exp_f32_e32 v115, v115
	v_lshlrev_b32_e32 v116, 16, v227
	v_and_b32_e32 v117, 0xffff0000, v227
	v_add_f32_e32 v114, 1.0, v114
	v_add_f32_e32 v115, 1.0, v115
	v_rcp_f32_e32 v114, v114
	v_rcp_f32_e32 v115, v115
	v_add_f32_e32 v118, v159, v119
	v_pk_mul_f32 v[174:175], v[114:115], v[116:117]
	s_nop 0
	v_add_f32_e32 v114, v174, v118
	v_mul_f32_e32 v118, v159, v159
	v_mov_b32_e32 v116, v174
	v_mov_b32_e32 v117, v159
	v_pk_add_f32 v[0:1], v[118:119], v[0:1] op_sel_hi:[0,1]
	v_pk_fma_f32 v[0:1], v[116:117], v[116:117], v[0:1]
	v_pk_mul_f32 v[116:117], v[174:175], v[174:175]
	v_pk_mov_b32 v[0:1], v[174:175], v[0:1] op_sel:[1,0]
	v_mov_b32_e32 v115, v117
	v_pk_add_f32 v[0:1], v[0:1], v[114:115]
	ds_bpermute_b32 v114, v216, v0
	ds_bpermute_b32 v115, v216, v1
	s_waitcnt lgkmcnt(0)
	v_pk_add_f32 v[114:115], v[0:1], v[114:115]
	ds_bpermute_b32 v116, v215, v114
	ds_bpermute_b32 v117, v215, v115
	s_and_saveexec_b64 s[0:1], vcc
	v_readlane_b32 s84, v255, 39
	v_readlane_b32 s85, v255, 40
	s_cbranch_execz .LBB0_747
	s_waitcnt lgkmcnt(0)
	v_pk_add_f32 v[0:1], v[114:115], v[116:117]
	ds_write_b64 v217, v[0:1] offset:128
.LBB0_747:
	s_or_b64 exec, exec, s[0:1]
	v_add_u32_e32 v0, 32, v150
	v_ashrrev_i32_e32 v1, 31, v0
	v_lshlrev_b64 v[196:197], 11, v[0:1]
	v_lshl_add_u64 v[0:1], s[16:17], 0, v[196:197]
	v_lshl_add_u64 v[0:1], v[146:147], 1, v[0:1]
	s_waitcnt lgkmcnt(0)
	s_nop 0
	v_mul_f32_e32 v0, 0xbfb8aa3b, v110
	v_mul_f32_e32 v1, 0xbfb8aa3b, v111
	v_exp_f32_e32 v0, v0
	v_exp_f32_e32 v1, v1
	v_mul_f32_e32 v106, 0xbfb8aa3b, v106
	v_mul_f32_e32 v107, 0xbfb8aa3b, v107
	v_add_f32_e32 v0, 1.0, v0
	v_add_f32_e32 v1, 1.0, v1
	v_rcp_f32_e32 v0, v0
	v_rcp_f32_e32 v1, v1
	v_exp_f32_e32 v106, v106
	v_exp_f32_e32 v107, v107
	v_add_f32_e32 v106, 1.0, v106
	v_add_f32_e32 v107, 1.0, v107
	v_rcp_f32_e32 v106, v106
	v_rcp_f32_e32 v107, v107
	s_waitcnt vmcnt(5)
	v_lshlrev_b32_e32 v110, 16, v228
	v_and_b32_e32 v111, 0xffff0000, v228
	v_pk_mul_f32 v[162:163], v[0:1], v[110:111]
	v_mul_f32_e32 v1, 0xbfb8aa3b, v113
	v_add_f32_e32 v0, 0, v162
	v_add_f32_e32 v114, v163, v0
	v_mul_f32_e32 v0, 0xbfb8aa3b, v112
	v_exp_f32_e32 v0, v0
	v_exp_f32_e32 v1, v1
	v_lshlrev_b32_e32 v110, 16, v229
	v_and_b32_e32 v111, 0xffff0000, v229
	v_add_f32_e32 v0, 1.0, v0
	v_add_f32_e32 v1, 1.0, v1
	v_rcp_f32_e32 v0, v0
	v_rcp_f32_e32 v1, v1
	s_nop 0
	v_pk_mul_f32 v[166:167], v[0:1], v[110:111]
	v_mul_f32_e32 v110, v162, v162
	v_add_f32_e32 v111, v166, v114
	v_mov_b32_e32 v0, v166
	v_mov_b32_e32 v1, v162
	v_fmac_f32_e32 v110, v163, v163
	v_pk_fma_f32 v[0:1], v[0:1], v[0:1], v[110:111] op_sel_hi:[1,1,0]
	v_add_f32_e32 v112, v167, v111
	v_lshlrev_b32_e32 v110, 16, v230
	v_and_b32_e32 v111, 0xffff0000, v230
	v_pk_mul_f32 v[172:173], v[106:107], v[110:111]
	v_mul_f32_e32 v110, v167, v167
	v_add_f32_e32 v111, v172, v112
	v_mov_b32_e32 v106, v172
	v_mov_b32_e32 v107, v167
	v_pk_add_f32 v[0:1], v[110:111], v[0:1] op_sel_hi:[0,1]
	v_pk_fma_f32 v[0:1], v[106:107], v[106:107], v[0:1]
	v_mul_f32_e32 v106, 0xbfb8aa3b, v108
	v_mul_f32_e32 v107, 0xbfb8aa3b, v109
	v_exp_f32_e32 v106, v106
	v_exp_f32_e32 v107, v107
	v_lshlrev_b32_e32 v108, 16, v231
	v_and_b32_e32 v109, 0xffff0000, v231
	v_add_f32_e32 v106, 1.0, v106
	v_add_f32_e32 v107, 1.0, v107
	v_rcp_f32_e32 v106, v106
	v_rcp_f32_e32 v107, v107
	v_add_f32_e32 v110, v173, v111
	v_pk_mul_f32 v[184:185], v[106:107], v[108:109]
	s_nop 0
	v_add_f32_e32 v106, v184, v110
	v_mul_f32_e32 v110, v173, v173
	v_mov_b32_e32 v108, v184
	v_mov_b32_e32 v109, v173
	v_pk_add_f32 v[0:1], v[110:111], v[0:1] op_sel_hi:[0,1]
	v_pk_fma_f32 v[0:1], v[108:109], v[108:109], v[0:1]
	v_pk_mul_f32 v[108:109], v[184:185], v[184:185]
	v_pk_mov_b32 v[0:1], v[184:185], v[0:1] op_sel:[1,0]
	v_mov_b32_e32 v107, v109
	v_pk_add_f32 v[0:1], v[0:1], v[106:107]
	ds_bpermute_b32 v106, v216, v0
	ds_bpermute_b32 v107, v216, v1
	s_waitcnt lgkmcnt(0)
	v_pk_add_f32 v[106:107], v[0:1], v[106:107]
	ds_bpermute_b32 v108, v215, v106
	ds_bpermute_b32 v109, v215, v107
	s_and_saveexec_b64 s[0:1], vcc
	s_cbranch_execz .LBB0_749
	s_waitcnt lgkmcnt(0)
	v_pk_add_f32 v[0:1], v[106:107], v[108:109]
	ds_write_b64 v217, v[0:1] offset:256
.LBB0_749:
	s_or_b64 exec, exec, s[0:1]
	v_add_u32_e32 v0, 48, v150
	v_ashrrev_i32_e32 v1, 31, v0
	v_lshlrev_b64 v[198:199], 11, v[0:1]
	v_lshl_add_u64 v[0:1], s[16:17], 0, v[198:199]
	v_lshl_add_u64 v[0:1], v[146:147], 1, v[0:1]
	s_waitcnt lgkmcnt(0)
	s_nop 0
	v_mul_f32_e32 v0, 0xbfb8aa3b, v102
	v_mul_f32_e32 v1, 0xbfb8aa3b, v103
	v_exp_f32_e32 v0, v0
	v_exp_f32_e32 v1, v1
	v_mul_f32_e32 v98, 0xbfb8aa3b, v98
	v_mul_f32_e32 v99, 0xbfb8aa3b, v99
	v_add_f32_e32 v0, 1.0, v0
	v_add_f32_e32 v1, 1.0, v1
	v_rcp_f32_e32 v0, v0
	v_rcp_f32_e32 v1, v1
	v_exp_f32_e32 v98, v98
	v_exp_f32_e32 v99, v99
	v_add_f32_e32 v98, 1.0, v98
	v_add_f32_e32 v99, 1.0, v99
	v_rcp_f32_e32 v98, v98
	v_rcp_f32_e32 v99, v99
	s_waitcnt vmcnt(4)
	v_lshlrev_b32_e32 v102, 16, v232
	v_and_b32_e32 v103, 0xffff0000, v232
	v_pk_mul_f32 v[114:115], v[0:1], v[102:103]
	v_mul_f32_e32 v1, 0xbfb8aa3b, v105
	v_add_f32_e32 v0, 0, v114
	v_add_f32_e32 v106, v115, v0
	v_mul_f32_e32 v0, 0xbfb8aa3b, v104
	v_exp_f32_e32 v0, v0
	v_exp_f32_e32 v1, v1
	v_lshlrev_b32_e32 v102, 16, v233
	v_and_b32_e32 v103, 0xffff0000, v233
	v_add_f32_e32 v0, 1.0, v0
	v_add_f32_e32 v1, 1.0, v1
	v_rcp_f32_e32 v0, v0
	v_rcp_f32_e32 v1, v1
	s_nop 0
	v_pk_mul_f32 v[116:117], v[0:1], v[102:103]
	v_mul_f32_e32 v102, v114, v114
	v_add_f32_e32 v103, v116, v106
	v_mov_b32_e32 v0, v116
	v_mov_b32_e32 v1, v114
	v_fmac_f32_e32 v102, v115, v115
	v_pk_fma_f32 v[0:1], v[0:1], v[0:1], v[102:103] op_sel_hi:[1,1,0]
	v_add_f32_e32 v104, v117, v103
	v_lshlrev_b32_e32 v102, 16, v234
	v_and_b32_e32 v103, 0xffff0000, v234
	v_pk_mul_f32 v[118:119], v[98:99], v[102:103]
	v_mul_f32_e32 v102, v117, v117
	v_add_f32_e32 v103, v118, v104
	v_mov_b32_e32 v98, v118
	v_mov_b32_e32 v99, v117
	v_pk_add_f32 v[0:1], v[102:103], v[0:1] op_sel_hi:[0,1]
	v_pk_fma_f32 v[0:1], v[98:99], v[98:99], v[0:1]
	v_mul_f32_e32 v98, 0xbfb8aa3b, v100
	v_mul_f32_e32 v99, 0xbfb8aa3b, v101
	v_exp_f32_e32 v98, v98
	v_exp_f32_e32 v99, v99
	v_lshlrev_b32_e32 v100, 16, v235
	v_and_b32_e32 v101, 0xffff0000, v235
	v_add_f32_e32 v98, 1.0, v98
	v_add_f32_e32 v99, 1.0, v99
	v_rcp_f32_e32 v98, v98
	v_rcp_f32_e32 v99, v99
	v_add_f32_e32 v102, v119, v103
	v_pk_mul_f32 v[120:121], v[98:99], v[100:101]
	s_nop 0
	v_add_f32_e32 v98, v120, v102
	v_mul_f32_e32 v102, v119, v119
	v_mov_b32_e32 v100, v120
	v_mov_b32_e32 v101, v119
	v_pk_add_f32 v[0:1], v[102:103], v[0:1] op_sel_hi:[0,1]
	v_pk_fma_f32 v[0:1], v[100:101], v[100:101], v[0:1]
	v_pk_mul_f32 v[100:101], v[120:121], v[120:121]
	v_pk_mov_b32 v[0:1], v[120:121], v[0:1] op_sel:[1,0]
	v_mov_b32_e32 v99, v101
	v_pk_add_f32 v[0:1], v[0:1], v[98:99]
	ds_bpermute_b32 v98, v216, v0
	ds_bpermute_b32 v99, v216, v1
	s_waitcnt lgkmcnt(0)
	v_pk_add_f32 v[98:99], v[0:1], v[98:99]
	ds_bpermute_b32 v100, v215, v98
	ds_bpermute_b32 v101, v215, v99
	s_and_saveexec_b64 s[0:1], vcc
	s_cbranch_execz .LBB0_751
	s_waitcnt lgkmcnt(0)
	v_pk_add_f32 v[0:1], v[98:99], v[100:101]
	ds_write_b64 v217, v[0:1] offset:384
.LBB0_751:
	s_or_b64 exec, exec, s[0:1]
	v_add_u32_e32 v0, 0x80, v150
	v_ashrrev_i32_e32 v1, 31, v0
	v_lshlrev_b64 v[200:201], 11, v[0:1]
	v_lshl_add_u64 v[0:1], s[16:17], 0, v[200:201]
	v_lshl_add_u64 v[0:1], v[146:147], 1, v[0:1]
	s_waitcnt lgkmcnt(0)
	s_nop 0
	v_mul_f32_e32 v0, 0xbfb8aa3b, v94
	v_mul_f32_e32 v1, 0xbfb8aa3b, v95
	v_exp_f32_e32 v0, v0
	v_exp_f32_e32 v1, v1
	v_mul_f32_e32 v90, 0xbfb8aa3b, v90
	v_mul_f32_e32 v91, 0xbfb8aa3b, v91
	v_add_f32_e32 v0, 1.0, v0
	v_add_f32_e32 v1, 1.0, v1
	v_rcp_f32_e32 v0, v0
	v_rcp_f32_e32 v1, v1
	v_exp_f32_e32 v90, v90
	v_exp_f32_e32 v91, v91
	v_add_f32_e32 v90, 1.0, v90
	v_add_f32_e32 v91, 1.0, v91
	v_rcp_f32_e32 v90, v90
	v_rcp_f32_e32 v91, v91
	s_waitcnt vmcnt(3)
	v_lshlrev_b32_e32 v94, 16, v236
	v_and_b32_e32 v95, 0xffff0000, v236
	v_pk_mul_f32 v[152:153], v[0:1], v[94:95]
	v_mul_f32_e32 v1, 0xbfb8aa3b, v97
	v_add_f32_e32 v0, 0, v152
	v_add_f32_e32 v98, v153, v0
	v_mul_f32_e32 v0, 0xbfb8aa3b, v96
	v_exp_f32_e32 v0, v0
	v_exp_f32_e32 v1, v1
	v_lshlrev_b32_e32 v94, 16, v237
	v_and_b32_e32 v95, 0xffff0000, v237
	v_add_f32_e32 v0, 1.0, v0
	v_add_f32_e32 v1, 1.0, v1
	v_rcp_f32_e32 v0, v0
	v_rcp_f32_e32 v1, v1
	s_nop 0
	v_pk_mul_f32 v[160:161], v[0:1], v[94:95]
	v_mul_f32_e32 v94, v152, v152
	v_add_f32_e32 v95, v160, v98
	v_mov_b32_e32 v0, v160
	v_mov_b32_e32 v1, v152
	v_fmac_f32_e32 v94, v153, v153
	v_pk_fma_f32 v[0:1], v[0:1], v[0:1], v[94:95] op_sel_hi:[1,1,0]
	v_add_f32_e32 v96, v161, v95
	v_lshlrev_b32_e32 v94, 16, v238
	v_and_b32_e32 v95, 0xffff0000, v238
	v_pk_mul_f32 v[164:165], v[90:91], v[94:95]
	v_mul_f32_e32 v94, v161, v161
	v_add_f32_e32 v95, v164, v96
	v_mov_b32_e32 v90, v164
	v_mov_b32_e32 v91, v161
	v_pk_add_f32 v[0:1], v[94:95], v[0:1] op_sel_hi:[0,1]
	v_pk_fma_f32 v[0:1], v[90:91], v[90:91], v[0:1]
	v_mul_f32_e32 v90, 0xbfb8aa3b, v92
	v_mul_f32_e32 v91, 0xbfb8aa3b, v93
	v_exp_f32_e32 v90, v90
	v_exp_f32_e32 v91, v91
	v_lshlrev_b32_e32 v92, 16, v239
	v_and_b32_e32 v93, 0xffff0000, v239
	v_add_f32_e32 v90, 1.0, v90
	v_add_f32_e32 v91, 1.0, v91
	v_rcp_f32_e32 v90, v90
	v_rcp_f32_e32 v91, v91
	v_add_f32_e32 v94, v165, v95
	v_pk_mul_f32 v[178:179], v[90:91], v[92:93]
	s_nop 0
	v_add_f32_e32 v90, v178, v94
	v_mul_f32_e32 v94, v165, v165
	v_mov_b32_e32 v92, v178
	v_mov_b32_e32 v93, v165
	v_pk_add_f32 v[0:1], v[94:95], v[0:1] op_sel_hi:[0,1]
	v_pk_fma_f32 v[0:1], v[92:93], v[92:93], v[0:1]
	v_pk_mul_f32 v[92:93], v[178:179], v[178:179]
	v_pk_mov_b32 v[0:1], v[178:179], v[0:1] op_sel:[1,0]
	v_mov_b32_e32 v91, v93
	v_pk_add_f32 v[0:1], v[0:1], v[90:91]
	ds_bpermute_b32 v90, v216, v0
	ds_bpermute_b32 v91, v216, v1
	s_waitcnt lgkmcnt(0)
	v_pk_add_f32 v[90:91], v[0:1], v[90:91]
	ds_bpermute_b32 v92, v215, v90
	ds_bpermute_b32 v93, v215, v91
	s_and_saveexec_b64 s[0:1], vcc
	s_cbranch_execz .LBB0_753
	s_waitcnt lgkmcnt(0)
	v_pk_add_f32 v[0:1], v[90:91], v[92:93]
	ds_write_b64 v217, v[0:1] offset:512
.LBB0_753:
	s_or_b64 exec, exec, s[0:1]
	v_add_u32_e32 v0, 0x90, v150
	v_ashrrev_i32_e32 v1, 31, v0
	v_lshlrev_b64 v[94:95], 11, v[0:1]
	v_lshl_add_u64 v[0:1], s[16:17], 0, v[94:95]
	v_lshl_add_u64 v[0:1], v[146:147], 1, v[0:1]
	s_waitcnt lgkmcnt(0)
	s_nop 0
	v_mul_f32_e32 v0, 0xbfb8aa3b, v86
	v_mul_f32_e32 v1, 0xbfb8aa3b, v87
	v_exp_f32_e32 v0, v0
	v_exp_f32_e32 v1, v1
	v_mul_f32_e32 v82, 0xbfb8aa3b, v82
	v_mul_f32_e32 v83, 0xbfb8aa3b, v83
	v_add_f32_e32 v0, 1.0, v0
	v_add_f32_e32 v1, 1.0, v1
	v_rcp_f32_e32 v0, v0
	v_rcp_f32_e32 v1, v1
	v_exp_f32_e32 v82, v82
	v_exp_f32_e32 v83, v83
	v_add_f32_e32 v82, 1.0, v82
	v_add_f32_e32 v83, 1.0, v83
	v_rcp_f32_e32 v82, v82
	v_rcp_f32_e32 v83, v83
	s_waitcnt vmcnt(2)
	v_lshlrev_b32_e32 v86, 16, v242
	v_and_b32_e32 v87, 0xffff0000, v242
	v_pk_mul_f32 v[170:171], v[0:1], v[86:87]
	v_mul_f32_e32 v1, 0xbfb8aa3b, v89
	v_add_f32_e32 v0, 0, v170
	v_add_f32_e32 v90, v171, v0
	v_mul_f32_e32 v0, 0xbfb8aa3b, v88
	v_exp_f32_e32 v0, v0
	v_exp_f32_e32 v1, v1
	v_lshlrev_b32_e32 v86, 16, v243
	v_and_b32_e32 v87, 0xffff0000, v243
	v_add_f32_e32 v0, 1.0, v0
	v_add_f32_e32 v1, 1.0, v1
	v_rcp_f32_e32 v0, v0
	v_rcp_f32_e32 v1, v1
	s_nop 0
	v_pk_mul_f32 v[176:177], v[0:1], v[86:87]
	v_mul_f32_e32 v86, v170, v170
	v_add_f32_e32 v87, v176, v90
	v_mov_b32_e32 v0, v176
	v_mov_b32_e32 v1, v170
	v_fmac_f32_e32 v86, v171, v171
	v_pk_fma_f32 v[0:1], v[0:1], v[0:1], v[86:87] op_sel_hi:[1,1,0]
	v_add_f32_e32 v88, v177, v87
	v_lshlrev_b32_e32 v86, 16, v244
	v_and_b32_e32 v87, 0xffff0000, v244
	v_pk_mul_f32 v[180:181], v[82:83], v[86:87]
	v_mul_f32_e32 v86, v177, v177
	v_add_f32_e32 v87, v180, v88
	v_mov_b32_e32 v82, v180
	v_mov_b32_e32 v83, v177
	v_pk_add_f32 v[0:1], v[86:87], v[0:1] op_sel_hi:[0,1]
	v_pk_fma_f32 v[0:1], v[82:83], v[82:83], v[0:1]
	v_mul_f32_e32 v82, 0xbfb8aa3b, v84
	v_mul_f32_e32 v83, 0xbfb8aa3b, v85
	v_exp_f32_e32 v82, v82
	v_exp_f32_e32 v83, v83
	v_lshlrev_b32_e32 v84, 16, v245
	v_and_b32_e32 v85, 0xffff0000, v245
	v_add_f32_e32 v82, 1.0, v82
	v_add_f32_e32 v83, 1.0, v83
	v_rcp_f32_e32 v82, v82
	v_rcp_f32_e32 v83, v83
	v_add_f32_e32 v86, v181, v87
	v_pk_mul_f32 v[190:191], v[82:83], v[84:85]
	s_nop 0
	v_add_f32_e32 v82, v190, v86
	v_mul_f32_e32 v86, v181, v181
	v_mov_b32_e32 v84, v190
	v_mov_b32_e32 v85, v181
	v_pk_add_f32 v[0:1], v[86:87], v[0:1] op_sel_hi:[0,1]
	v_pk_fma_f32 v[0:1], v[84:85], v[84:85], v[0:1]
	v_pk_mul_f32 v[84:85], v[190:191], v[190:191]
	v_pk_mov_b32 v[0:1], v[190:191], v[0:1] op_sel:[1,0]
	v_mov_b32_e32 v83, v85
	v_pk_add_f32 v[0:1], v[0:1], v[82:83]
	ds_bpermute_b32 v82, v216, v0
	ds_bpermute_b32 v83, v216, v1
	s_waitcnt lgkmcnt(0)
	v_pk_add_f32 v[82:83], v[0:1], v[82:83]
	ds_bpermute_b32 v84, v215, v82
	ds_bpermute_b32 v85, v215, v83
	s_and_saveexec_b64 s[0:1], vcc
	s_cbranch_execz .LBB0_755
	s_waitcnt lgkmcnt(0)
	v_pk_add_f32 v[0:1], v[82:83], v[84:85]
	ds_write_b64 v217, v[0:1] offset:640
.LBB0_755:
	s_or_b64 exec, exec, s[0:1]
	v_add_u32_e32 v0, 0xa0, v150
	v_ashrrev_i32_e32 v1, 31, v0
	v_lshlrev_b64 v[86:87], 11, v[0:1]
	v_lshl_add_u64 v[0:1], s[16:17], 0, v[86:87]
	v_lshl_add_u64 v[0:1], v[146:147], 1, v[0:1]
	s_waitcnt lgkmcnt(0)
	s_nop 0
	v_mul_f32_e32 v0, 0xbfb8aa3b, v78
	v_mul_f32_e32 v1, 0xbfb8aa3b, v79
	v_exp_f32_e32 v0, v0
	v_exp_f32_e32 v1, v1
	v_mul_f32_e32 v74, 0xbfb8aa3b, v74
	v_mul_f32_e32 v75, 0xbfb8aa3b, v75
	v_add_f32_e32 v0, 1.0, v0
	v_add_f32_e32 v1, 1.0, v1
	v_rcp_f32_e32 v0, v0
	v_rcp_f32_e32 v1, v1
	v_exp_f32_e32 v74, v74
	v_exp_f32_e32 v75, v75
	v_add_f32_e32 v74, 1.0, v74
	v_add_f32_e32 v75, 1.0, v75
	v_rcp_f32_e32 v74, v74
	v_rcp_f32_e32 v75, v75
	s_waitcnt vmcnt(1)
	v_lshlrev_b32_e32 v78, 16, v246
	v_and_b32_e32 v79, 0xffff0000, v246
	v_pk_mul_f32 v[182:183], v[0:1], v[78:79]
	v_mul_f32_e32 v1, 0xbfb8aa3b, v81
	v_add_f32_e32 v0, 0, v182
	v_add_f32_e32 v82, v183, v0
	v_mul_f32_e32 v0, 0xbfb8aa3b, v80
	v_exp_f32_e32 v0, v0
	v_exp_f32_e32 v1, v1
	v_lshlrev_b32_e32 v78, 16, v247
	v_and_b32_e32 v79, 0xffff0000, v247
	v_add_f32_e32 v0, 1.0, v0
	v_add_f32_e32 v1, 1.0, v1
	v_rcp_f32_e32 v0, v0
	v_rcp_f32_e32 v1, v1
	s_nop 0
	v_pk_mul_f32 v[186:187], v[0:1], v[78:79]
	v_mul_f32_e32 v78, v182, v182
	v_add_f32_e32 v79, v186, v82
	v_mov_b32_e32 v0, v186
	v_mov_b32_e32 v1, v182
	v_fmac_f32_e32 v78, v183, v183
	v_pk_fma_f32 v[0:1], v[0:1], v[0:1], v[78:79] op_sel_hi:[1,1,0]
	v_add_f32_e32 v80, v187, v79
	v_lshlrev_b32_e32 v78, 16, v248
	v_and_b32_e32 v79, 0xffff0000, v248
	v_pk_mul_f32 v[188:189], v[74:75], v[78:79]
	v_mul_f32_e32 v78, v187, v187
	v_add_f32_e32 v79, v188, v80
	v_mov_b32_e32 v74, v188
	v_mov_b32_e32 v75, v187
	v_pk_add_f32 v[0:1], v[78:79], v[0:1] op_sel_hi:[0,1]
	v_pk_fma_f32 v[0:1], v[74:75], v[74:75], v[0:1]
	v_mul_f32_e32 v74, 0xbfb8aa3b, v76
	v_mul_f32_e32 v75, 0xbfb8aa3b, v77
	v_exp_f32_e32 v74, v74
	v_exp_f32_e32 v75, v75
	v_lshlrev_b32_e32 v76, 16, v249
	v_and_b32_e32 v77, 0xffff0000, v249
	v_add_f32_e32 v74, 1.0, v74
	v_add_f32_e32 v75, 1.0, v75
	v_rcp_f32_e32 v74, v74
	v_rcp_f32_e32 v75, v75
	v_add_f32_e32 v78, v189, v79
	v_pk_mul_f32 v[194:195], v[74:75], v[76:77]
	s_nop 0
	v_add_f32_e32 v74, v194, v78
	v_mul_f32_e32 v78, v189, v189
	v_mov_b32_e32 v76, v194
	v_mov_b32_e32 v77, v189
	v_pk_add_f32 v[0:1], v[78:79], v[0:1] op_sel_hi:[0,1]
	v_pk_fma_f32 v[0:1], v[76:77], v[76:77], v[0:1]
	v_pk_mul_f32 v[76:77], v[194:195], v[194:195]
	v_pk_mov_b32 v[0:1], v[194:195], v[0:1] op_sel:[1,0]
	v_mov_b32_e32 v75, v77
	v_pk_add_f32 v[0:1], v[0:1], v[74:75]
	ds_bpermute_b32 v74, v216, v0
	ds_bpermute_b32 v75, v216, v1
	s_waitcnt lgkmcnt(0)
	v_pk_add_f32 v[74:75], v[0:1], v[74:75]
	ds_bpermute_b32 v76, v215, v74
	ds_bpermute_b32 v77, v215, v75
	s_and_saveexec_b64 s[0:1], vcc
	s_cbranch_execz .LBB0_757
	s_waitcnt lgkmcnt(0)
	v_pk_add_f32 v[0:1], v[74:75], v[76:77]
	ds_write_b64 v217, v[0:1] offset:768
.LBB0_757:
	s_or_b64 exec, exec, s[0:1]
	v_add_u32_e32 v0, 0xb0, v150
	v_ashrrev_i32_e32 v1, 31, v0
	v_lshlrev_b64 v[78:79], 11, v[0:1]
	v_lshl_add_u64 v[0:1], s[16:17], 0, v[78:79]
	v_lshl_add_u64 v[0:1], v[146:147], 1, v[0:1]
	s_waitcnt lgkmcnt(0)
	s_nop 0
	v_mul_f32_e32 v0, 0xbfb8aa3b, v70
	v_mul_f32_e32 v1, 0xbfb8aa3b, v71
	v_exp_f32_e32 v0, v0
	v_exp_f32_e32 v1, v1
	v_mul_f32_e32 v66, 0xbfb8aa3b, v66
	v_mul_f32_e32 v67, 0xbfb8aa3b, v67
	v_add_f32_e32 v0, 1.0, v0
	v_add_f32_e32 v1, 1.0, v1
	v_rcp_f32_e32 v0, v0
	v_rcp_f32_e32 v1, v1
	v_exp_f32_e32 v66, v66
	v_exp_f32_e32 v67, v67
	v_add_f32_e32 v66, 1.0, v66
	v_add_f32_e32 v67, 1.0, v67
	v_rcp_f32_e32 v66, v66
	v_rcp_f32_e32 v67, v67
	s_waitcnt vmcnt(0)
	v_lshlrev_b32_e32 v70, 16, v250
	v_and_b32_e32 v71, 0xffff0000, v250
	v_pk_mul_f32 v[122:123], v[0:1], v[70:71]
	v_mul_f32_e32 v1, 0xbfb8aa3b, v73
	v_add_f32_e32 v0, 0, v122
	v_add_f32_e32 v74, v123, v0
	v_mul_f32_e32 v0, 0xbfb8aa3b, v72
	v_exp_f32_e32 v0, v0
	v_exp_f32_e32 v1, v1
	v_lshlrev_b32_e32 v70, 16, v251
	v_and_b32_e32 v71, 0xffff0000, v251
	v_add_f32_e32 v0, 1.0, v0
	v_add_f32_e32 v1, 1.0, v1
	v_rcp_f32_e32 v0, v0
	v_rcp_f32_e32 v1, v1
	s_nop 0
	v_pk_mul_f32 v[124:125], v[0:1], v[70:71]
	v_mul_f32_e32 v70, v122, v122
	v_add_f32_e32 v71, v124, v74
	v_mov_b32_e32 v0, v124
	v_mov_b32_e32 v1, v122
	v_fmac_f32_e32 v70, v123, v123
	v_pk_fma_f32 v[0:1], v[0:1], v[0:1], v[70:71] op_sel_hi:[1,1,0]
	v_add_f32_e32 v72, v125, v71
	v_lshlrev_b32_e32 v70, 16, v252
	v_and_b32_e32 v71, 0xffff0000, v252
	v_pk_mul_f32 v[150:151], v[66:67], v[70:71]
	v_mul_f32_e32 v70, v125, v125
	v_add_f32_e32 v71, v150, v72
	v_mov_b32_e32 v66, v150
	v_mov_b32_e32 v67, v125
	v_pk_add_f32 v[0:1], v[70:71], v[0:1] op_sel_hi:[0,1]
	v_pk_fma_f32 v[0:1], v[66:67], v[66:67], v[0:1]
	v_mul_f32_e32 v66, 0xbfb8aa3b, v68
	v_mul_f32_e32 v67, 0xbfb8aa3b, v69
	v_exp_f32_e32 v66, v66
	v_exp_f32_e32 v67, v67
	v_lshlrev_b32_e32 v68, 16, v253
	v_and_b32_e32 v69, 0xffff0000, v253
	v_add_f32_e32 v66, 1.0, v66
	v_add_f32_e32 v67, 1.0, v67
	v_rcp_f32_e32 v66, v66
	v_rcp_f32_e32 v67, v67
	v_add_f32_e32 v70, v151, v71
	v_pk_mul_f32 v[168:169], v[66:67], v[68:69]
	s_nop 0
	v_add_f32_e32 v66, v168, v70
	v_mul_f32_e32 v70, v151, v151
	v_mov_b32_e32 v68, v168
	v_mov_b32_e32 v69, v151
	v_pk_add_f32 v[0:1], v[70:71], v[0:1] op_sel_hi:[0,1]
	v_pk_fma_f32 v[0:1], v[68:69], v[68:69], v[0:1]
	v_pk_mul_f32 v[68:69], v[168:169], v[168:169]
	v_pk_mov_b32 v[0:1], v[168:169], v[0:1] op_sel:[1,0]
	v_mov_b32_e32 v67, v69
	v_pk_add_f32 v[0:1], v[0:1], v[66:67]
	ds_bpermute_b32 v66, v216, v0
	ds_bpermute_b32 v67, v216, v1
	s_waitcnt lgkmcnt(0)
	v_pk_add_f32 v[66:67], v[0:1], v[66:67]
	ds_bpermute_b32 v68, v215, v66
	ds_bpermute_b32 v69, v215, v67
	s_and_saveexec_b64 s[0:1], vcc
	s_cbranch_execz .LBB0_759
	s_waitcnt lgkmcnt(0)
	v_pk_add_f32 v[0:1], v[66:67], v[68:69]
	ds_write_b64 v217, v[0:1] offset:896

.LBB0_1594:
	s_lshl_b32 s6, s68, 7
	s_or_b32 s6, s6, s77
	s_lshl_b32 s24, s70, 8
	v_lshl_add_u32 v142, v148, 3, s6
	s_add_i32 s6, s24, s76
	v_add_u32_e32 v180, s6, v214
	v_ashrrev_i32_e32 v181, 31, v180
	v_lshlrev_b64 v[192:193], 11, v[180:181]
	v_ashrrev_i32_e32 v143, 31, v142
	v_lshl_add_u64 v[0:1], s[10:11], 0, v[192:193]
	v_lshl_add_u64 v[0:1], v[142:143], 1, v[0:1]
	global_load_dwordx4 v[220:223], v[0:1], off
	v_add_u32_e32 v224, 16, v180
	v_ashrrev_i32_e32 v225, 31, v224
	v_lshlrev_b64 v[224:225], 11, v[224:225]
	v_lshl_add_u64 v[224:225], s[10:11], 0, v[224:225]
	v_lshl_add_u64 v[224:225], v[142:143], 1, v[224:225]
	global_load_dwordx4 v[224:227], v[224:225], off
	v_add_u32_e32 v228, 32, v180
	v_ashrrev_i32_e32 v229, 31, v228
	v_lshlrev_b64 v[228:229], 11, v[228:229]
	v_lshl_add_u64 v[228:229], s[10:11], 0, v[228:229]
	v_lshl_add_u64 v[228:229], v[142:143], 1, v[228:229]
	global_load_dwordx4 v[228:231], v[228:229], off
	v_add_u32_e32 v232, 48, v180
	v_ashrrev_i32_e32 v233, 31, v232
	v_lshlrev_b64 v[232:233], 11, v[232:233]
	v_lshl_add_u64 v[232:233], s[10:11], 0, v[232:233]
	v_lshl_add_u64 v[232:233], v[142:143], 1, v[232:233]
	global_load_dwordx4 v[232:235], v[232:233], off
	v_add_u32_e32 v236, 128, v180
	v_ashrrev_i32_e32 v237, 31, v236
	v_lshlrev_b64 v[236:237], 11, v[236:237]
	v_lshl_add_u64 v[236:237], s[10:11], 0, v[236:237]
	v_lshl_add_u64 v[236:237], v[142:143], 1, v[236:237]
	global_load_dwordx4 v[236:239], v[236:237], off
	v_add_u32_e32 v242, 144, v180
	v_ashrrev_i32_e32 v243, 31, v242
	v_lshlrev_b64 v[242:243], 11, v[242:243]
	v_lshl_add_u64 v[242:243], s[10:11], 0, v[242:243]
	v_lshl_add_u64 v[242:243], v[142:143], 1, v[242:243]
	global_load_dwordx4 v[242:245], v[242:243], off
	v_add_u32_e32 v246, 160, v180
	v_ashrrev_i32_e32 v247, 31, v246
	v_lshlrev_b64 v[246:247], 11, v[246:247]
	v_lshl_add_u64 v[246:247], s[10:11], 0, v[246:247]
	v_lshl_add_u64 v[246:247], v[142:143], 1, v[246:247]
	global_load_dwordx4 v[246:249], v[246:247], off
	v_add_u32_e32 v250, 176, v180
	v_ashrrev_i32_e32 v251, 31, v250
	v_lshlrev_b64 v[250:251], 11, v[250:251]
	v_lshl_add_u64 v[250:251], s[10:11], 0, v[250:251]
	v_lshl_add_u64 v[250:251], v[142:143], 1, v[250:251]
	global_load_dwordx4 v[250:253], v[250:251], off
	v_and_b32_e32 v1, 64, v211
	v_mul_f32_e32 v126, 0xbfb8aa3b, v126
	v_mul_f32_e32 v127, 0xbfb8aa3b, v127
	v_mul_f32_e32 v128, 0xbfb8aa3b, v128
	v_mul_f32_e32 v129, 0xbfb8aa3b, v129
	v_add_u32_e32 v149, 64, v1
	v_exp_f32_e32 v1, v126
	v_exp_f32_e32 v126, v127
	v_xor_b32_e32 v0, 16, v211
	v_mul_f32_e32 v122, 0xbfb8aa3b, v122
	v_mul_f32_e32 v123, 0xbfb8aa3b, v123
	v_exp_f32_e32 v127, v128
	v_exp_f32_e32 v128, v129
	v_exp_f32_e32 v122, v122
	v_exp_f32_e32 v123, v123
	v_cmp_lt_i32_e32 vcc, v0, v149
	v_mul_f32_e32 v124, 0xbfb8aa3b, v124
	v_mul_f32_e32 v125, 0xbfb8aa3b, v125
	v_cndmask_b32_e32 v0, v211, v0, vcc
	v_exp_f32_e32 v124, v124
	v_exp_f32_e32 v125, v125
	v_lshlrev_b32_e32 v215, 2, v0
	v_add_f32_e32 v0, 1.0, v1
	v_add_f32_e32 v1, 1.0, v126
	v_add_f32_e32 v126, 1.0, v127
	v_add_f32_e32 v127, 1.0, v128
	v_rcp_f32_e32 v0, v0
	v_rcp_f32_e32 v1, v1
	v_add_f32_e32 v128, 1.0, v122
	v_add_f32_e32 v129, 1.0, v123
	v_rcp_f32_e32 v122, v126
	v_rcp_f32_e32 v123, v127
	v_add_f32_e32 v150, 1.0, v124
	v_add_f32_e32 v151, 1.0, v125
	v_rcp_f32_e32 v124, v128
	v_rcp_f32_e32 v125, v129
	v_rcp_f32_e32 v150, v150
	v_rcp_f32_e32 v151, v151
	s_waitcnt vmcnt(7)
	v_lshlrev_b32_e32 v126, 16, v220
	v_and_b32_e32 v127, 0xffff0000, v220
	v_lshlrev_b32_e32 v144, 16, v221
	v_and_b32_e32 v145, 0xffff0000, v221
	v_pk_mul_f32 v[128:129], v[0:1], v[126:127]
	v_pk_mul_f32 v[126:127], v[122:123], v[144:145]
	v_add_f32_e32 v145, 0, v128
	v_mul_f32_e32 v144, v128, v128
	v_add_f32_e32 v145, v129, v145
	v_lshlrev_b32_e32 v152, 16, v222
	v_and_b32_e32 v153, 0xffff0000, v222
	v_lshlrev_b32_e32 v146, 16, v223
	v_and_b32_e32 v147, 0xffff0000, v223
	v_mov_b32_e32 v0, v126
	v_mov_b32_e32 v1, v128
	v_fmac_f32_e32 v144, v129, v129
	v_add_f32_e32 v145, v126, v145
	v_pk_mul_f32 v[124:125], v[124:125], v[152:153]
	v_pk_mul_f32 v[122:123], v[150:151], v[146:147]
	v_mul_f32_e32 v150, v127, v127
	v_pk_fma_f32 v[0:1], v[0:1], v[0:1], v[144:145] op_sel_hi:[1,1,0]
	v_mov_b32_e32 v146, v124
	v_mov_b32_e32 v147, v127
	v_pk_add_f32 v[0:1], v[150:151], v[0:1] op_sel_hi:[0,1]
	v_mul_f32_e32 v154, v125, v125
	v_add_f32_e32 v144, v127, v145
	v_pk_fma_f32 v[0:1], v[146:147], v[146:147], v[0:1]
	v_mov_b32_e32 v152, v122
	v_mov_b32_e32 v153, v125
	v_add_f32_e32 v144, v124, v144
	v_pk_add_f32 v[0:1], v[154:155], v[0:1] op_sel_hi:[0,1]
	v_pk_mul_f32 v[156:157], v[122:123], v[122:123]
	v_add_f32_e32 v144, v125, v144
	v_pk_fma_f32 v[0:1], v[152:153], v[152:153], v[0:1]
	v_add_f32_e32 v156, v122, v144
	v_pk_mov_b32 v[0:1], v[122:123], v[0:1] op_sel:[1,0]
	v_xor_b32_e32 v146, 32, v211
	v_pk_add_f32 v[0:1], v[0:1], v[156:157]
	ds_bpermute_b32 v144, v215, v0
	ds_bpermute_b32 v145, v215, v1
	v_cmp_lt_i32_e32 vcc, v146, v149
	v_add_u32_e32 v150, s80, v214
	s_waitcnt lgkmcnt(0)
	v_pk_add_f32 v[144:145], v[0:1], v[144:145]
	v_cndmask_b32_e32 v146, v211, v146, vcc
	v_lshlrev_b32_e32 v216, 2, v146
	ds_bpermute_b32 v146, v216, v144
	ds_bpermute_b32 v147, v216, v145
	v_cmp_eq_u32_e32 vcc, 0, v148
	s_and_saveexec_b64 s[6:7], vcc
	s_cbranch_execz .LBB0_1596
	v_lshl_add_u32 v0, v150, 3, 0
	v_add_u32_e32 v148, 0x20000, v0
	s_waitcnt lgkmcnt(0)
	v_pk_add_f32 v[0:1], v[144:145], v[146:147]
	ds_write_b64 v148, v[0:1]
.LBB0_1596:
	s_or_b64 exec, exec, s[6:7]
	v_add_u32_e32 v0, 16, v180
	v_ashrrev_i32_e32 v1, 31, v0
	v_lshlrev_b64 v[194:195], 11, v[0:1]
	v_lshl_add_u64 v[0:1], s[10:11], 0, v[194:195]
	v_lshl_add_u64 v[0:1], v[142:143], 1, v[0:1]
	s_waitcnt lgkmcnt(0)
	s_nop 0
	v_mul_f32_e32 v0, 0xbfb8aa3b, v118
	v_mul_f32_e32 v1, 0xbfb8aa3b, v119
	v_mul_f32_e32 v118, 0xbfb8aa3b, v120
	v_mul_f32_e32 v119, 0xbfb8aa3b, v121
	v_exp_f32_e32 v0, v0
	v_exp_f32_e32 v1, v1
	v_mul_f32_e32 v114, 0xbfb8aa3b, v114
	v_mul_f32_e32 v115, 0xbfb8aa3b, v115
	v_exp_f32_e32 v118, v118
	v_exp_f32_e32 v119, v119
	v_exp_f32_e32 v114, v114
	v_exp_f32_e32 v115, v115
	v_mul_f32_e32 v116, 0xbfb8aa3b, v116
	v_mul_f32_e32 v117, 0xbfb8aa3b, v117
	v_exp_f32_e32 v116, v116
	v_exp_f32_e32 v117, v117
	v_add_f32_e32 v0, 1.0, v0
	v_add_f32_e32 v1, 1.0, v1
	v_add_f32_e32 v118, 1.0, v118
	v_add_f32_e32 v119, 1.0, v119
	v_rcp_f32_e32 v0, v0
	v_rcp_f32_e32 v1, v1
	v_add_f32_e32 v120, 1.0, v114
	v_add_f32_e32 v121, 1.0, v115
	v_rcp_f32_e32 v114, v118
	v_rcp_f32_e32 v115, v119
	v_add_f32_e32 v148, 1.0, v116
	v_add_f32_e32 v149, 1.0, v117
	v_rcp_f32_e32 v116, v120
	v_rcp_f32_e32 v117, v121
	v_rcp_f32_e32 v118, v148
	v_rcp_f32_e32 v119, v149
	v_lshl_add_u32 v217, v150, 3, s81
	s_waitcnt vmcnt(6)
	v_lshlrev_b32_e32 v120, 16, v224
	v_and_b32_e32 v121, 0xffff0000, v224
	v_lshlrev_b32_e32 v144, 16, v225
	v_and_b32_e32 v145, 0xffff0000, v225
	v_pk_mul_f32 v[152:153], v[0:1], v[120:121]
	v_pk_mul_f32 v[148:149], v[114:115], v[144:145]
	v_add_f32_e32 v115, 0, v152
	v_mul_f32_e32 v114, v152, v152
	v_add_f32_e32 v115, v153, v115
	v_lshlrev_b32_e32 v154, 16, v226
	v_and_b32_e32 v155, 0xffff0000, v226
	v_lshlrev_b32_e32 v156, 16, v227
	v_and_b32_e32 v157, 0xffff0000, v227
	v_mov_b32_e32 v0, v148
	v_mov_b32_e32 v1, v152
	v_fmac_f32_e32 v114, v153, v153
	v_add_f32_e32 v115, v148, v115
	v_pk_mul_f32 v[146:147], v[116:117], v[154:155]
	v_pk_mul_f32 v[144:145], v[118:119], v[156:157]
	v_mul_f32_e32 v118, v149, v149
	v_pk_fma_f32 v[0:1], v[0:1], v[0:1], v[114:115] op_sel_hi:[1,1,0]
	v_mov_b32_e32 v116, v146
	v_mov_b32_e32 v117, v149
	v_pk_add_f32 v[0:1], v[118:119], v[0:1] op_sel_hi:[0,1]
	v_mul_f32_e32 v154, v147, v147
	v_add_f32_e32 v114, v149, v115
	v_pk_fma_f32 v[0:1], v[116:117], v[116:117], v[0:1]
	v_mov_b32_e32 v120, v144
	v_mov_b32_e32 v121, v147
	v_add_f32_e32 v114, v146, v114
	v_pk_add_f32 v[0:1], v[154:155], v[0:1] op_sel_hi:[0,1]
	v_pk_mul_f32 v[156:157], v[144:145], v[144:145]
	v_add_f32_e32 v114, v147, v114
	v_pk_fma_f32 v[0:1], v[120:121], v[120:121], v[0:1]
	v_add_f32_e32 v156, v144, v114
	v_pk_mov_b32 v[0:1], v[144:145], v[0:1] op_sel:[1,0]
	s_nop 0
	v_pk_add_f32 v[0:1], v[0:1], v[156:157]
	ds_bpermute_b32 v114, v215, v0
	ds_bpermute_b32 v115, v215, v1
	s_waitcnt lgkmcnt(0)
	v_pk_add_f32 v[114:115], v[0:1], v[114:115]
	ds_bpermute_b32 v116, v216, v114
	ds_bpermute_b32 v117, v216, v115
	s_and_saveexec_b64 s[6:7], vcc
	s_cbranch_execz .LBB0_1598
	s_waitcnt lgkmcnt(0)
	v_pk_add_f32 v[0:1], v[114:115], v[116:117]
	ds_write_b64 v217, v[0:1] offset:128
.LBB0_1598:
	s_or_b64 exec, exec, s[6:7]
	v_add_u32_e32 v0, 32, v180
	v_ashrrev_i32_e32 v1, 31, v0
	v_lshlrev_b64 v[196:197], 11, v[0:1]
	v_lshl_add_u64 v[0:1], s[10:11], 0, v[196:197]
	v_lshl_add_u64 v[0:1], v[142:143], 1, v[0:1]
	s_waitcnt lgkmcnt(0)
	s_nop 0
	v_mul_f32_e32 v0, 0xbfb8aa3b, v110
	v_mul_f32_e32 v1, 0xbfb8aa3b, v111
	v_mul_f32_e32 v110, 0xbfb8aa3b, v112
	v_mul_f32_e32 v111, 0xbfb8aa3b, v113
	v_exp_f32_e32 v0, v0
	v_exp_f32_e32 v1, v1
	v_mul_f32_e32 v106, 0xbfb8aa3b, v106
	v_mul_f32_e32 v107, 0xbfb8aa3b, v107
	v_exp_f32_e32 v110, v110
	v_exp_f32_e32 v111, v111
	v_exp_f32_e32 v106, v106
	v_exp_f32_e32 v107, v107
	v_mul_f32_e32 v108, 0xbfb8aa3b, v108
	v_mul_f32_e32 v109, 0xbfb8aa3b, v109
	v_exp_f32_e32 v108, v108
	v_exp_f32_e32 v109, v109
	v_add_f32_e32 v0, 1.0, v0
	v_add_f32_e32 v1, 1.0, v1
	v_add_f32_e32 v110, 1.0, v110
	v_add_f32_e32 v111, 1.0, v111
	v_rcp_f32_e32 v0, v0
	v_rcp_f32_e32 v1, v1
	v_add_f32_e32 v112, 1.0, v106
	v_add_f32_e32 v113, 1.0, v107
	v_rcp_f32_e32 v106, v110
	v_rcp_f32_e32 v107, v111
	v_add_f32_e32 v118, 1.0, v108
	v_add_f32_e32 v119, 1.0, v109
	v_rcp_f32_e32 v108, v112
	v_rcp_f32_e32 v109, v113
	v_rcp_f32_e32 v110, v118
	v_rcp_f32_e32 v111, v119
	s_waitcnt vmcnt(5)
	v_lshlrev_b32_e32 v112, 16, v228
	v_and_b32_e32 v113, 0xffff0000, v228
	v_lshlrev_b32_e32 v114, 16, v229
	v_and_b32_e32 v115, 0xffff0000, v229
	v_pk_mul_f32 v[168:169], v[0:1], v[112:113]
	v_pk_mul_f32 v[164:165], v[106:107], v[114:115]
	v_add_f32_e32 v107, 0, v168
	v_mul_f32_e32 v106, v168, v168
	v_add_f32_e32 v107, v169, v107
	v_lshlrev_b32_e32 v118, 16, v230
	v_and_b32_e32 v119, 0xffff0000, v230
	v_lshlrev_b32_e32 v116, 16, v231
	v_and_b32_e32 v117, 0xffff0000, v231
	v_mov_b32_e32 v0, v164
	v_mov_b32_e32 v1, v168
	v_fmac_f32_e32 v106, v169, v169
	v_add_f32_e32 v107, v164, v107
	v_pk_mul_f32 v[162:163], v[108:109], v[118:119]
	v_pk_mul_f32 v[160:161], v[110:111], v[116:117]
	v_mul_f32_e32 v110, v165, v165
	v_pk_fma_f32 v[0:1], v[0:1], v[0:1], v[106:107] op_sel_hi:[1,1,0]
	v_mov_b32_e32 v108, v162
	v_mov_b32_e32 v109, v165
	v_pk_add_f32 v[0:1], v[110:111], v[0:1] op_sel_hi:[0,1]
	v_mul_f32_e32 v114, v163, v163
	v_add_f32_e32 v106, v165, v107
	v_pk_fma_f32 v[0:1], v[108:109], v[108:109], v[0:1]
	v_mov_b32_e32 v112, v160
	v_mov_b32_e32 v113, v163
	v_add_f32_e32 v106, v162, v106
	v_pk_add_f32 v[0:1], v[114:115], v[0:1] op_sel_hi:[0,1]
	v_pk_mul_f32 v[116:117], v[160:161], v[160:161]
	v_add_f32_e32 v106, v163, v106
	v_pk_fma_f32 v[0:1], v[112:113], v[112:113], v[0:1]
	v_add_f32_e32 v116, v160, v106
	v_pk_mov_b32 v[0:1], v[160:161], v[0:1] op_sel:[1,0]
	s_nop 0
	v_pk_add_f32 v[0:1], v[0:1], v[116:117]
	ds_bpermute_b32 v106, v215, v0
	ds_bpermute_b32 v107, v215, v1
	s_waitcnt lgkmcnt(0)
	v_pk_add_f32 v[106:107], v[0:1], v[106:107]
	ds_bpermute_b32 v108, v216, v106
	ds_bpermute_b32 v109, v216, v107
	s_and_saveexec_b64 s[6:7], vcc
	s_cbranch_execz .LBB0_1600
	s_waitcnt lgkmcnt(0)
	v_pk_add_f32 v[0:1], v[106:107], v[108:109]
	ds_write_b64 v217, v[0:1] offset:256
.LBB0_1600:
	s_or_b64 exec, exec, s[6:7]
	v_add_u32_e32 v0, 48, v180
	v_ashrrev_i32_e32 v1, 31, v0
	v_lshlrev_b64 v[198:199], 11, v[0:1]
	v_lshl_add_u64 v[0:1], s[10:11], 0, v[198:199]
	v_lshl_add_u64 v[0:1], v[142:143], 1, v[0:1]
	s_waitcnt lgkmcnt(0)
	s_nop 0
	v_mul_f32_e32 v0, 0xbfb8aa3b, v102
	v_mul_f32_e32 v1, 0xbfb8aa3b, v103
	v_mul_f32_e32 v102, 0xbfb8aa3b, v104
	v_mul_f32_e32 v103, 0xbfb8aa3b, v105
	v_exp_f32_e32 v0, v0
	v_exp_f32_e32 v1, v1
	v_mul_f32_e32 v98, 0xbfb8aa3b, v98
	v_mul_f32_e32 v99, 0xbfb8aa3b, v99
	v_exp_f32_e32 v102, v102
	v_exp_f32_e32 v103, v103
	v_exp_f32_e32 v98, v98
	v_exp_f32_e32 v99, v99
	v_mul_f32_e32 v100, 0xbfb8aa3b, v100
	v_mul_f32_e32 v101, 0xbfb8aa3b, v101
	v_exp_f32_e32 v100, v100
	v_exp_f32_e32 v101, v101
	v_add_f32_e32 v0, 1.0, v0
	v_add_f32_e32 v1, 1.0, v1
	v_add_f32_e32 v102, 1.0, v102
	v_add_f32_e32 v103, 1.0, v103
	v_rcp_f32_e32 v0, v0
	v_rcp_f32_e32 v1, v1
	v_add_f32_e32 v104, 1.0, v98
	v_add_f32_e32 v105, 1.0, v99
	v_rcp_f32_e32 v98, v102
	v_rcp_f32_e32 v99, v103
	v_add_f32_e32 v110, 1.0, v100
	v_add_f32_e32 v111, 1.0, v101
	v_rcp_f32_e32 v100, v104
	v_rcp_f32_e32 v101, v105
	v_rcp_f32_e32 v102, v110
	v_rcp_f32_e32 v103, v111
	s_waitcnt vmcnt(4)
	v_lshlrev_b32_e32 v104, 16, v232
	v_and_b32_e32 v105, 0xffff0000, v232
	v_lshlrev_b32_e32 v106, 16, v233
	v_and_b32_e32 v107, 0xffff0000, v233
	v_pk_mul_f32 v[186:187], v[0:1], v[104:105]
	v_pk_mul_f32 v[182:183], v[98:99], v[106:107]
	v_add_f32_e32 v99, 0, v186
	v_mul_f32_e32 v98, v186, v186
	v_add_f32_e32 v99, v187, v99
	v_lshlrev_b32_e32 v110, 16, v234
	v_and_b32_e32 v111, 0xffff0000, v234
	v_lshlrev_b32_e32 v108, 16, v235
	v_and_b32_e32 v109, 0xffff0000, v235
	v_mov_b32_e32 v0, v182
	v_mov_b32_e32 v1, v186
	v_fmac_f32_e32 v98, v187, v187
	v_add_f32_e32 v99, v182, v99
	v_pk_mul_f32 v[178:179], v[100:101], v[110:111]
	v_pk_mul_f32 v[174:175], v[102:103], v[108:109]
	v_mul_f32_e32 v102, v183, v183
	v_pk_fma_f32 v[0:1], v[0:1], v[0:1], v[98:99] op_sel_hi:[1,1,0]
	v_mov_b32_e32 v100, v178
	v_mov_b32_e32 v101, v183
	v_pk_add_f32 v[0:1], v[102:103], v[0:1] op_sel_hi:[0,1]
	v_mul_f32_e32 v106, v179, v179
	v_add_f32_e32 v98, v183, v99
	v_pk_fma_f32 v[0:1], v[100:101], v[100:101], v[0:1]
	v_mov_b32_e32 v104, v174
	v_mov_b32_e32 v105, v179
	v_add_f32_e32 v98, v178, v98
	v_pk_add_f32 v[0:1], v[106:107], v[0:1] op_sel_hi:[0,1]
	v_pk_mul_f32 v[108:109], v[174:175], v[174:175]
	v_add_f32_e32 v98, v179, v98
	v_pk_fma_f32 v[0:1], v[104:105], v[104:105], v[0:1]
	v_add_f32_e32 v108, v174, v98
	v_pk_mov_b32 v[0:1], v[174:175], v[0:1] op_sel:[1,0]
	s_nop 0
	v_pk_add_f32 v[0:1], v[0:1], v[108:109]
	ds_bpermute_b32 v98, v215, v0
	ds_bpermute_b32 v99, v215, v1
	s_waitcnt lgkmcnt(0)
	v_pk_add_f32 v[98:99], v[0:1], v[98:99]
	ds_bpermute_b32 v100, v216, v98
	ds_bpermute_b32 v101, v216, v99
	s_and_saveexec_b64 s[6:7], vcc
	s_cbranch_execz .LBB0_1602
	s_waitcnt lgkmcnt(0)
	v_pk_add_f32 v[0:1], v[98:99], v[100:101]
	ds_write_b64 v217, v[0:1] offset:384
.LBB0_1602:
	s_or_b64 exec, exec, s[6:7]
	v_add_u32_e32 v0, 0x80, v180
	v_ashrrev_i32_e32 v1, 31, v0
	v_lshlrev_b64 v[200:201], 11, v[0:1]
	v_lshl_add_u64 v[0:1], s[10:11], 0, v[200:201]
	v_lshl_add_u64 v[0:1], v[142:143], 1, v[0:1]
	s_waitcnt lgkmcnt(0)
	s_nop 0
	v_mul_f32_e32 v0, 0xbfb8aa3b, v94
	v_mul_f32_e32 v1, 0xbfb8aa3b, v95
	v_mul_f32_e32 v94, 0xbfb8aa3b, v96
	v_mul_f32_e32 v95, 0xbfb8aa3b, v97
	v_exp_f32_e32 v0, v0
	v_exp_f32_e32 v1, v1
	v_mul_f32_e32 v90, 0xbfb8aa3b, v90
	v_mul_f32_e32 v91, 0xbfb8aa3b, v91
	v_exp_f32_e32 v94, v94
	v_exp_f32_e32 v95, v95
	v_exp_f32_e32 v90, v90
	v_exp_f32_e32 v91, v91
	v_mul_f32_e32 v92, 0xbfb8aa3b, v92
	v_mul_f32_e32 v93, 0xbfb8aa3b, v93
	v_exp_f32_e32 v92, v92
	v_exp_f32_e32 v93, v93
	v_add_f32_e32 v0, 1.0, v0
	v_add_f32_e32 v1, 1.0, v1
	v_add_f32_e32 v94, 1.0, v94
	v_add_f32_e32 v95, 1.0, v95
	v_rcp_f32_e32 v0, v0
	v_rcp_f32_e32 v1, v1
	v_add_f32_e32 v96, 1.0, v90
	v_add_f32_e32 v97, 1.0, v91
	v_rcp_f32_e32 v90, v94
	v_rcp_f32_e32 v91, v95
	v_add_f32_e32 v102, 1.0, v92
	v_add_f32_e32 v103, 1.0, v93
	v_rcp_f32_e32 v92, v96
	v_rcp_f32_e32 v93, v97
	v_rcp_f32_e32 v94, v102
	v_rcp_f32_e32 v95, v103
	s_waitcnt vmcnt(3)
	v_lshlrev_b32_e32 v96, 16, v236
	v_and_b32_e32 v97, 0xffff0000, v236
	v_lshlrev_b32_e32 v98, 16, v237
	v_and_b32_e32 v99, 0xffff0000, v237
	v_pk_mul_f32 v[120:121], v[0:1], v[96:97]
	v_pk_mul_f32 v[118:119], v[90:91], v[98:99]
	v_add_f32_e32 v91, 0, v120
	v_mul_f32_e32 v90, v120, v120
	v_add_f32_e32 v91, v121, v91
	v_lshlrev_b32_e32 v102, 16, v238
	v_and_b32_e32 v103, 0xffff0000, v238
	v_lshlrev_b32_e32 v100, 16, v239
	v_and_b32_e32 v101, 0xffff0000, v239
	v_mov_b32_e32 v0, v118
	v_mov_b32_e32 v1, v120
	v_fmac_f32_e32 v90, v121, v121
	v_add_f32_e32 v91, v118, v91
	v_pk_mul_f32 v[116:117], v[92:93], v[102:103]
	v_pk_mul_f32 v[114:115], v[94:95], v[100:101]
	v_mul_f32_e32 v94, v119, v119
	v_pk_fma_f32 v[0:1], v[0:1], v[0:1], v[90:91] op_sel_hi:[1,1,0]
	v_mov_b32_e32 v92, v116
	v_mov_b32_e32 v93, v119
	v_pk_add_f32 v[0:1], v[94:95], v[0:1] op_sel_hi:[0,1]
	v_mul_f32_e32 v98, v117, v117
	v_add_f32_e32 v90, v119, v91
	v_pk_fma_f32 v[0:1], v[92:93], v[92:93], v[0:1]
	v_mov_b32_e32 v96, v114
	v_mov_b32_e32 v97, v117
	v_add_f32_e32 v90, v116, v90
	v_pk_add_f32 v[0:1], v[98:99], v[0:1] op_sel_hi:[0,1]
	v_pk_mul_f32 v[100:101], v[114:115], v[114:115]
	v_add_f32_e32 v90, v117, v90
	v_pk_fma_f32 v[0:1], v[96:97], v[96:97], v[0:1]
	v_add_f32_e32 v100, v114, v90
	v_pk_mov_b32 v[0:1], v[114:115], v[0:1] op_sel:[1,0]
	s_nop 0
	v_pk_add_f32 v[0:1], v[0:1], v[100:101]
	ds_bpermute_b32 v90, v215, v0
	ds_bpermute_b32 v91, v215, v1
	s_waitcnt lgkmcnt(0)
	v_pk_add_f32 v[90:91], v[0:1], v[90:91]
	ds_bpermute_b32 v92, v216, v90
	ds_bpermute_b32 v93, v216, v91
	s_and_saveexec_b64 s[6:7], vcc
	s_cbranch_execz .LBB0_1604
	s_waitcnt lgkmcnt(0)
	v_pk_add_f32 v[0:1], v[90:91], v[92:93]
	ds_write_b64 v217, v[0:1] offset:512
.LBB0_1604:
	s_or_b64 exec, exec, s[6:7]
	v_add_u32_e32 v0, 0x90, v180
	v_ashrrev_i32_e32 v1, 31, v0
	v_lshlrev_b64 v[90:91], 11, v[0:1]
	v_lshl_add_u64 v[0:1], s[10:11], 0, v[90:91]
	v_lshl_add_u64 v[0:1], v[142:143], 1, v[0:1]
	s_waitcnt lgkmcnt(0)
	s_nop 0
	v_mul_f32_e32 v0, 0xbfb8aa3b, v86
	v_mul_f32_e32 v1, 0xbfb8aa3b, v87
	v_mul_f32_e32 v86, 0xbfb8aa3b, v88
	v_mul_f32_e32 v87, 0xbfb8aa3b, v89
	v_exp_f32_e32 v0, v0
	v_exp_f32_e32 v1, v1
	v_mul_f32_e32 v82, 0xbfb8aa3b, v82
	v_mul_f32_e32 v83, 0xbfb8aa3b, v83
	v_exp_f32_e32 v86, v86
	v_exp_f32_e32 v87, v87
	v_exp_f32_e32 v82, v82
	v_exp_f32_e32 v83, v83
	v_mul_f32_e32 v84, 0xbfb8aa3b, v84
	v_mul_f32_e32 v85, 0xbfb8aa3b, v85
	v_exp_f32_e32 v84, v84
	v_exp_f32_e32 v85, v85
	v_add_f32_e32 v0, 1.0, v0
	v_add_f32_e32 v1, 1.0, v1
	v_add_f32_e32 v86, 1.0, v86
	v_add_f32_e32 v87, 1.0, v87
	v_rcp_f32_e32 v0, v0
	v_rcp_f32_e32 v1, v1
	v_add_f32_e32 v88, 1.0, v82
	v_add_f32_e32 v89, 1.0, v83
	v_rcp_f32_e32 v82, v86
	v_rcp_f32_e32 v83, v87
	v_add_f32_e32 v96, 1.0, v84
	v_add_f32_e32 v97, 1.0, v85
	v_rcp_f32_e32 v84, v88
	v_rcp_f32_e32 v85, v89
	v_rcp_f32_e32 v86, v96
	v_rcp_f32_e32 v87, v97
	s_waitcnt vmcnt(2)
	v_lshlrev_b32_e32 v88, 16, v242
	v_and_b32_e32 v89, 0xffff0000, v242
	v_lshlrev_b32_e32 v92, 16, v243
	v_and_b32_e32 v93, 0xffff0000, v243
	v_pk_mul_f32 v[158:159], v[0:1], v[88:89]
	v_pk_mul_f32 v[156:157], v[82:83], v[92:93]
	v_add_f32_e32 v83, 0, v158
	v_mul_f32_e32 v82, v158, v158
	v_add_f32_e32 v83, v159, v83
	v_lshlrev_b32_e32 v96, 16, v244
	v_and_b32_e32 v97, 0xffff0000, v244
	v_lshlrev_b32_e32 v94, 16, v245
	v_and_b32_e32 v95, 0xffff0000, v245
	v_mov_b32_e32 v0, v156
	v_mov_b32_e32 v1, v158
	v_fmac_f32_e32 v82, v159, v159
	v_add_f32_e32 v83, v156, v83
	v_pk_mul_f32 v[154:155], v[84:85], v[96:97]
	v_pk_mul_f32 v[150:151], v[86:87], v[94:95]
	v_mul_f32_e32 v86, v157, v157
	v_pk_fma_f32 v[0:1], v[0:1], v[0:1], v[82:83] op_sel_hi:[1,1,0]
	v_mov_b32_e32 v84, v154
	v_mov_b32_e32 v85, v157
	v_pk_add_f32 v[0:1], v[86:87], v[0:1] op_sel_hi:[0,1]
	v_mul_f32_e32 v92, v155, v155
	v_add_f32_e32 v82, v157, v83
	v_pk_fma_f32 v[0:1], v[84:85], v[84:85], v[0:1]
	v_mov_b32_e32 v88, v150
	v_mov_b32_e32 v89, v155
	v_add_f32_e32 v82, v154, v82
	v_pk_add_f32 v[0:1], v[92:93], v[0:1] op_sel_hi:[0,1]
	v_pk_mul_f32 v[94:95], v[150:151], v[150:151]
	v_add_f32_e32 v82, v155, v82
	v_pk_fma_f32 v[0:1], v[88:89], v[88:89], v[0:1]
	v_add_f32_e32 v94, v150, v82
	v_pk_mov_b32 v[0:1], v[150:151], v[0:1] op_sel:[1,0]
	s_nop 0
	v_pk_add_f32 v[0:1], v[0:1], v[94:95]
	ds_bpermute_b32 v82, v215, v0
	ds_bpermute_b32 v83, v215, v1
	s_waitcnt lgkmcnt(0)
	v_pk_add_f32 v[82:83], v[0:1], v[82:83]
	ds_bpermute_b32 v84, v216, v82
	ds_bpermute_b32 v85, v216, v83
	s_and_saveexec_b64 s[6:7], vcc
	s_cbranch_execz .LBB0_1606
	s_waitcnt lgkmcnt(0)
	v_pk_add_f32 v[0:1], v[82:83], v[84:85]
	ds_write_b64 v217, v[0:1] offset:640
.LBB0_1606:
	s_or_b64 exec, exec, s[6:7]
	v_add_u32_e32 v0, 0xa0, v180
	v_ashrrev_i32_e32 v1, 31, v0
	v_lshlrev_b64 v[82:83], 11, v[0:1]
	v_lshl_add_u64 v[0:1], s[10:11], 0, v[82:83]
	v_lshl_add_u64 v[0:1], v[142:143], 1, v[0:1]
	s_waitcnt lgkmcnt(0)
	s_nop 0
	v_mul_f32_e32 v0, 0xbfb8aa3b, v78
	v_mul_f32_e32 v1, 0xbfb8aa3b, v79
	v_mul_f32_e32 v78, 0xbfb8aa3b, v80
	v_mul_f32_e32 v79, 0xbfb8aa3b, v81
	v_exp_f32_e32 v0, v0
	v_exp_f32_e32 v1, v1
	v_mul_f32_e32 v74, 0xbfb8aa3b, v74
	v_mul_f32_e32 v75, 0xbfb8aa3b, v75
	v_exp_f32_e32 v78, v78
	v_exp_f32_e32 v79, v79
	v_exp_f32_e32 v74, v74
	v_exp_f32_e32 v75, v75
	v_mul_f32_e32 v76, 0xbfb8aa3b, v76
	v_mul_f32_e32 v77, 0xbfb8aa3b, v77
	v_exp_f32_e32 v76, v76
	v_exp_f32_e32 v77, v77
	v_add_f32_e32 v0, 1.0, v0
	v_add_f32_e32 v1, 1.0, v1
	v_add_f32_e32 v78, 1.0, v78
	v_add_f32_e32 v79, 1.0, v79
	v_rcp_f32_e32 v0, v0
	v_rcp_f32_e32 v1, v1
	v_add_f32_e32 v80, 1.0, v74
	v_add_f32_e32 v81, 1.0, v75
	v_rcp_f32_e32 v74, v78
	v_rcp_f32_e32 v75, v79
	v_add_f32_e32 v88, 1.0, v76
	v_add_f32_e32 v89, 1.0, v77
	v_rcp_f32_e32 v76, v80
	v_rcp_f32_e32 v77, v81
	v_rcp_f32_e32 v78, v88
	v_rcp_f32_e32 v79, v89
	s_waitcnt vmcnt(1)
	v_lshlrev_b32_e32 v80, 16, v246
	v_and_b32_e32 v81, 0xffff0000, v246
	v_lshlrev_b32_e32 v84, 16, v247
	v_and_b32_e32 v85, 0xffff0000, v247
	v_pk_mul_f32 v[176:177], v[0:1], v[80:81]
	v_pk_mul_f32 v[172:173], v[74:75], v[84:85]
	v_add_f32_e32 v75, 0, v176
	v_mul_f32_e32 v74, v176, v176
	v_add_f32_e32 v75, v177, v75
	v_lshlrev_b32_e32 v88, 16, v248
	v_and_b32_e32 v89, 0xffff0000, v248
	v_lshlrev_b32_e32 v86, 16, v249
	v_and_b32_e32 v87, 0xffff0000, v249
	v_mov_b32_e32 v0, v172
	v_mov_b32_e32 v1, v176
	v_fmac_f32_e32 v74, v177, v177
	v_add_f32_e32 v75, v172, v75
	v_pk_mul_f32 v[170:171], v[76:77], v[88:89]
	v_pk_mul_f32 v[166:167], v[78:79], v[86:87]
	v_mul_f32_e32 v78, v173, v173
	v_pk_fma_f32 v[0:1], v[0:1], v[0:1], v[74:75] op_sel_hi:[1,1,0]
	v_mov_b32_e32 v76, v170
	v_mov_b32_e32 v77, v173
	v_pk_add_f32 v[0:1], v[78:79], v[0:1] op_sel_hi:[0,1]
	v_mul_f32_e32 v84, v171, v171
	v_add_f32_e32 v74, v173, v75
	v_pk_fma_f32 v[0:1], v[76:77], v[76:77], v[0:1]
	v_mov_b32_e32 v80, v166
	v_mov_b32_e32 v81, v171
	v_add_f32_e32 v74, v170, v74
	v_pk_add_f32 v[0:1], v[84:85], v[0:1] op_sel_hi:[0,1]
	v_pk_mul_f32 v[86:87], v[166:167], v[166:167]
	v_add_f32_e32 v74, v171, v74
	v_pk_fma_f32 v[0:1], v[80:81], v[80:81], v[0:1]
	v_add_f32_e32 v86, v166, v74
	v_pk_mov_b32 v[0:1], v[166:167], v[0:1] op_sel:[1,0]
	s_nop 0
	v_pk_add_f32 v[0:1], v[0:1], v[86:87]
	ds_bpermute_b32 v74, v215, v0
	ds_bpermute_b32 v75, v215, v1
	s_waitcnt lgkmcnt(0)
	v_pk_add_f32 v[74:75], v[0:1], v[74:75]
	ds_bpermute_b32 v76, v216, v74
	ds_bpermute_b32 v77, v216, v75
	s_and_saveexec_b64 s[6:7], vcc
	s_cbranch_execz .LBB0_1608
	s_waitcnt lgkmcnt(0)
	v_pk_add_f32 v[0:1], v[74:75], v[76:77]
	ds_write_b64 v217, v[0:1] offset:768
.LBB0_1608:
	s_or_b64 exec, exec, s[6:7]
	v_add_u32_e32 v0, 0xb0, v180
	v_ashrrev_i32_e32 v1, 31, v0
	v_lshlrev_b64 v[74:75], 11, v[0:1]
	v_lshl_add_u64 v[0:1], s[10:11], 0, v[74:75]
	v_lshl_add_u64 v[0:1], v[142:143], 1, v[0:1]
	s_waitcnt lgkmcnt(0)
	s_nop 0
	v_mul_f32_e32 v0, 0xbfb8aa3b, v70
	v_mul_f32_e32 v1, 0xbfb8aa3b, v71
	v_mul_f32_e32 v70, 0xbfb8aa3b, v72
	v_mul_f32_e32 v71, 0xbfb8aa3b, v73
	v_exp_f32_e32 v0, v0
	v_exp_f32_e32 v1, v1
	v_mul_f32_e32 v66, 0xbfb8aa3b, v66
	v_mul_f32_e32 v67, 0xbfb8aa3b, v67
	v_exp_f32_e32 v70, v70
	v_exp_f32_e32 v71, v71
	v_exp_f32_e32 v66, v66
	v_exp_f32_e32 v67, v67
	v_mul_f32_e32 v68, 0xbfb8aa3b, v68
	v_mul_f32_e32 v69, 0xbfb8aa3b, v69
	v_exp_f32_e32 v68, v68
	v_exp_f32_e32 v69, v69
	v_add_f32_e32 v0, 1.0, v0
	v_add_f32_e32 v1, 1.0, v1
	v_add_f32_e32 v70, 1.0, v70
	v_add_f32_e32 v71, 1.0, v71
	v_rcp_f32_e32 v0, v0
	v_rcp_f32_e32 v1, v1
	v_add_f32_e32 v72, 1.0, v66
	v_add_f32_e32 v73, 1.0, v67
	v_rcp_f32_e32 v66, v70
	v_rcp_f32_e32 v67, v71
	v_add_f32_e32 v80, 1.0, v68
	v_add_f32_e32 v81, 1.0, v69
	v_rcp_f32_e32 v68, v72
	v_rcp_f32_e32 v69, v73
	v_rcp_f32_e32 v70, v80
	v_rcp_f32_e32 v71, v81
	s_waitcnt vmcnt(0)
	v_lshlrev_b32_e32 v72, 16, v250
	v_and_b32_e32 v73, 0xffff0000, v250
	v_lshlrev_b32_e32 v76, 16, v251
	v_and_b32_e32 v77, 0xffff0000, v251
	v_pk_mul_f32 v[190:191], v[0:1], v[72:73]
	v_pk_mul_f32 v[188:189], v[66:67], v[76:77]
	v_add_f32_e32 v67, 0, v190
	v_mul_f32_e32 v66, v190, v190
	v_add_f32_e32 v67, v191, v67
	v_lshlrev_b32_e32 v80, 16, v252
	v_and_b32_e32 v81, 0xffff0000, v252
	v_lshlrev_b32_e32 v78, 16, v253
	v_and_b32_e32 v79, 0xffff0000, v253
	v_mov_b32_e32 v0, v188
	v_mov_b32_e32 v1, v190
	v_fmac_f32_e32 v66, v191, v191
	v_add_f32_e32 v67, v188, v67
	v_pk_mul_f32 v[184:185], v[68:69], v[80:81]
	v_pk_mul_f32 v[180:181], v[70:71], v[78:79]
	v_mul_f32_e32 v70, v189, v189
	v_pk_fma_f32 v[0:1], v[0:1], v[0:1], v[66:67] op_sel_hi:[1,1,0]
	v_mov_b32_e32 v68, v184
	v_mov_b32_e32 v69, v189
	v_pk_add_f32 v[0:1], v[70:71], v[0:1] op_sel_hi:[0,1]
	v_mul_f32_e32 v76, v185, v185
	v_add_f32_e32 v66, v189, v67
	v_pk_fma_f32 v[0:1], v[68:69], v[68:69], v[0:1]
	v_mov_b32_e32 v72, v180
	v_mov_b32_e32 v73, v185
	v_add_f32_e32 v66, v184, v66
	v_pk_add_f32 v[0:1], v[76:77], v[0:1] op_sel_hi:[0,1]
	v_pk_mul_f32 v[78:79], v[180:181], v[180:181]
	v_add_f32_e32 v66, v185, v66
	v_pk_fma_f32 v[0:1], v[72:73], v[72:73], v[0:1]
	v_add_f32_e32 v78, v180, v66
	v_pk_mov_b32 v[0:1], v[180:181], v[0:1] op_sel:[1,0]
	s_nop 0
	v_pk_add_f32 v[0:1], v[0:1], v[78:79]
	ds_bpermute_b32 v66, v215, v0
	ds_bpermute_b32 v67, v215, v1
	s_waitcnt lgkmcnt(0)
	v_pk_add_f32 v[66:67], v[0:1], v[66:67]
	ds_bpermute_b32 v68, v216, v66
	ds_bpermute_b32 v69, v216, v67
	s_and_saveexec_b64 s[6:7], vcc
	s_cbranch_execz .LBB0_1610
	s_waitcnt lgkmcnt(0)
	v_pk_add_f32 v[0:1], v[66:67], v[68:69]
	ds_write_b64 v217, v[0:1] offset:896
